# GEMM loops: 22 LDS-DMA loads take SGPR base + 32-bit VGPR offset directly (saddr form) instead of a per-load 64-bit v_lshl_add_u64 address
# baseline (speedup 1.0000x reference)
.LBB0_44:
	v_lshrrev_b32_e32 v17, 1, v242
	v_and_b32_e32 v17, 24, v17
	v_and_b32_e32 v16, 15, v242
	v_lshlrev_b32_e32 v18, 1, v17
	v_lshl_or_b32 v1, s6, 6, v16
	v_lshl_or_b32 v18, v16, 6, v18
	v_lshlrev_b32_e32 v16, 2, v16
	s_lshl_b32 s8, s6, 13
	v_and_b32_e32 v19, 32, v16
	v_bitop3_b32 v20, v18, s8, v19 bitop3:0xde
	s_lshl_b32 s8, s42, 5
	s_and_b32 s10, s8, 0x60
	s_add_i32 m0, s61, 0x18000
	v_lshl_add_u64 v[8:9], v[8:9], 0, s[82:83]
	s_lshl_b32 s8, s10, 7
	s_waitcnt vmcnt(2)
	s_barrier
	global_load_lds_dwordx4 v[8:9], off
	v_lshl_add_u64 v[6:7], v[6:7], 0, s[82:83]
	s_add_i32 m0, s61, 0x1a000
	s_add_i32 s65, s61, 0x8000
	s_add_i32 s66, s61, 0xa000
	v_bitop3_b32 v150, s8, v18, v19 bitop3:0xf6
	global_load_lds_dwordx4 v[6:7], off
	v_lshl_add_u64 v[2:3], v[2:3], 0, s[82:83]
	s_mov_b32 m0, s65
	s_add_u32 s8, s28, 0x40080
	global_load_lds_dwordx4 v[2:3], off
	v_lshl_add_u64 v[2:3], v[4:5], 0, s[82:83]
	s_mov_b32 m0, s66
	s_addc_u32 s9, s29, 0
	global_load_lds_dwordx4 v[2:3], off
	s_add_i32 m0, s61, 0x1c000
	s_nop 0
	global_load_lds_dwordx4 v130, s[8:9]
	s_add_i32 m0, s61, 0x1e000
	s_cmpk_lt_u32 s7, 0x100
	global_load_lds_dwordx4 v132, s[8:9]
	v_lshlrev_b32_e32 v2, 14, v14
	v_and_b32_e32 v2, 0xffff8000, v2
	v_lshl_add_u32 v2, v13, 11, v2
	v_and_b32_e32 v3, 1, v14
	v_lshl_or_b32 v2, v3, 6, v2
	v_lshl_add_u32 v138, v15, 1, v2
	v_lshlrev_b32_e32 v2, 14, v10
	s_cselect_b64 s[48:49], -1, 0
	s_lshl_b32 s6, s6, 8
	v_and_b32_e32 v2, 0xffff8000, v2
	s_waitcnt vmcnt(6)
	s_add_i32 s6, s6, 0
	v_lshl_add_u32 v2, v11, 11, v2
	v_and_b32_e32 v3, 1, v10
	s_add_i32 s6, s6, 0x20000
	v_lshl_or_b32 v2, v3, 6, v2
	v_readlane_b32 s8, v253, 35
	s_ashr_i32 s67, s4, 31
	v_add_u32_e32 v151, s6, v16
	v_or_b32_e32 v152, s10, v17
	v_mov_b32_e32 v139, v131
	v_lshl_add_u32 v140, v12, 1, v2
	v_mov_b32_e32 v141, v131
	s_mov_b32 s68, 0
	v_add_u32_e32 v153, 0, v20
	v_readlane_b32 s6, v251, 21
	s_mov_b32 s7, s8
	s_barrier
	v_readlane_b32 s9, v253, 36
	s_waitcnt vmcnt(0)
	s_branch .LBB0_47

.LBB0_50:
	s_add_u32 s8, s58, 0xfffc0080
	s_addc_u32 s9, s59, -1
	s_add_i32 s10, 0, 0x10000
	s_cmp_eq_u32 s85, 12
	s_cselect_b32 s41, s53, s9
	s_cselect_b32 s40, s69, s8
	s_cselect_b32 s29, s51, s84
	s_cselect_b32 s28, s72, s73
	s_add_i32 s11, 0, 0x14000
	v_add_u32_e32 v158, s10, v150
	v_add_u32_e32 v174, s11, v150
	ds_read_b128 v[142:145], v158
	ds_read_b128 v[146:149], v158 offset:1024
	ds_read_b128 v[154:157], v158 offset:2048
	ds_read_b128 v[158:161], v158 offset:3072
	ds_read_b128 v[162:165], v174
	ds_read_b128 v[166:169], v174 offset:1024
	ds_read_b128 v[170:173], v174 offset:2048
	ds_read_b128 v[174:177], v174 offset:3072
	s_add_i32 m0, s61, 0xc000
	ds_read_b128 v[178:181], v153
	ds_read_b128 v[182:185], v153 offset:1024
	ds_read_b128 v[186:189], v153 offset:2048
	ds_read_b128 v[190:193], v153 offset:3072
	ds_read_b128 v[194:197], v153 offset:4096
	ds_read_b128 v[198:201], v153 offset:5120
	ds_read_b128 v[202:205], v153 offset:6144
	ds_read_b128 v[206:209], v153 offset:7168
	global_load_lds_dwordx4 v138, s[58:59]
	s_add_i32 m0, s61, 0xe000
	s_nop 0
	global_load_lds_dwordx4 v140, s[58:59]
	s_waitcnt vmcnt(8)
	s_waitcnt lgkmcnt(0)
	s_setprio 1
	s_barrier
	v_mfma_f32_16x16x32_bf16 v[126:129], v[142:145], v[178:181], v[126:129]
	v_mfma_f32_16x16x32_bf16 v[118:121], v[154:157], v[178:181], v[118:121]
	v_mfma_f32_16x16x32_bf16 v[110:113], v[142:145], v[186:189], v[110:113]
	v_mfma_f32_16x16x32_bf16 v[102:105], v[154:157], v[186:189], v[102:105]
	v_mfma_f32_16x16x32_bf16 v[94:97], v[142:145], v[194:197], v[94:97]
	v_mfma_f32_16x16x32_bf16 v[86:89], v[154:157], v[194:197], v[86:89]
	v_mfma_f32_16x16x32_bf16 v[78:81], v[142:145], v[202:205], v[78:81]
	v_mfma_f32_16x16x32_bf16 v[70:73], v[154:157], v[202:205], v[70:73]
	v_mfma_f32_16x16x32_bf16 v[126:129], v[146:149], v[182:185], v[126:129]
	v_mfma_f32_16x16x32_bf16 v[118:121], v[158:161], v[182:185], v[118:121]
	v_mfma_f32_16x16x32_bf16 v[110:113], v[146:149], v[190:193], v[110:113]
	v_mfma_f32_16x16x32_bf16 v[102:105], v[158:161], v[190:193], v[102:105]
	v_mfma_f32_16x16x32_bf16 v[94:97], v[146:149], v[198:201], v[94:97]
	v_mfma_f32_16x16x32_bf16 v[86:89], v[158:161], v[198:201], v[86:89]
	v_mfma_f32_16x16x32_bf16 v[78:81], v[146:149], v[206:209], v[78:81]
	v_mfma_f32_16x16x32_bf16 v[70:73], v[158:161], v[206:209], v[70:73]
	v_mfma_f32_16x16x32_bf16 v[122:125], v[162:165], v[178:181], v[122:125]
	v_mfma_f32_16x16x32_bf16 v[114:117], v[170:173], v[178:181], v[114:117]
	v_mfma_f32_16x16x32_bf16 v[106:109], v[162:165], v[186:189], v[106:109]
	v_mfma_f32_16x16x32_bf16 v[98:101], v[170:173], v[186:189], v[98:101]
	v_mfma_f32_16x16x32_bf16 v[90:93], v[162:165], v[194:197], v[90:93]
	v_mfma_f32_16x16x32_bf16 v[82:85], v[170:173], v[194:197], v[82:85]
	v_mfma_f32_16x16x32_bf16 v[74:77], v[162:165], v[202:205], v[74:77]
	v_mfma_f32_16x16x32_bf16 v[66:69], v[170:173], v[202:205], v[66:69]
	v_mfma_f32_16x16x32_bf16 v[122:125], v[166:169], v[182:185], v[122:125]
	v_mfma_f32_16x16x32_bf16 v[114:117], v[174:177], v[182:185], v[114:117]
	v_mfma_f32_16x16x32_bf16 v[106:109], v[166:169], v[190:193], v[106:109]
	v_mfma_f32_16x16x32_bf16 v[98:101], v[174:177], v[190:193], v[98:101]
	v_mfma_f32_16x16x32_bf16 v[90:93], v[166:169], v[198:201], v[90:93]
	v_mfma_f32_16x16x32_bf16 v[82:85], v[174:177], v[198:201], v[82:85]
	v_mfma_f32_16x16x32_bf16 v[74:77], v[166:169], v[206:209], v[74:77]
	v_mfma_f32_16x16x32_bf16 v[66:69], v[174:177], v[206:209], v[66:69]
	s_barrier
	s_setprio 0
	s_add_i32 s8, s10, s31
	v_lshl_add_u64 v[210:211], s[28:29], 0, v[130:131]
	s_mov_b32 m0, s8
	ds_read_b128 v[178:181], v153 offset:16384
	ds_read_b128 v[182:185], v153 offset:17408
	ds_read_b128 v[186:189], v153 offset:18432
	ds_read_b128 v[190:193], v153 offset:19456
	ds_read_b128 v[194:197], v153 offset:20480
	ds_read_b128 v[198:201], v153 offset:21504
	ds_read_b128 v[202:205], v153 offset:22528
	ds_read_b128 v[206:209], v153 offset:23552
	global_load_lds_dwordx4 v[210:211], off
	s_add_i32 m0, s8, 0x2000
	s_add_u32 s8, s28, 0x40000
	v_lshl_add_u64 v[212:213], s[28:29], 0, v[132:133]
	s_addc_u32 s9, s29, 0
	s_add_i32 s10, s11, s31
	global_load_lds_dwordx4 v[212:213], off
	s_mov_b32 m0, s10
	v_lshl_add_u64 v[216:217], s[40:41], 0, v[134:135]
	global_load_lds_dwordx4 v130, s[8:9]
	s_add_i32 m0, s10, 0x2000
	s_nop 0
	global_load_lds_dwordx4 v132, s[8:9]
	v_lshl_add_u64 v[214:215], s[40:41], 0, v[136:137]
	s_mov_b32 m0, s61
	s_nop 0
	global_load_lds_dwordx4 v[214:215], off
	s_mov_b32 m0, s62
	s_nop 0
	global_load_lds_dwordx4 v[216:217], off
	s_waitcnt vmcnt(8)
	s_waitcnt lgkmcnt(0)
	s_setprio 1
	s_barrier
	v_mfma_f32_16x16x32_bf16 v[62:65], v[142:145], v[178:181], v[62:65]
	v_mfma_f32_16x16x32_bf16 v[54:57], v[154:157], v[178:181], v[54:57]
	v_mfma_f32_16x16x32_bf16 v[46:49], v[142:145], v[186:189], v[46:49]
	v_mfma_f32_16x16x32_bf16 v[38:41], v[154:157], v[186:189], v[38:41]
	v_mfma_f32_16x16x32_bf16 v[30:33], v[142:145], v[194:197], v[30:33]
	v_mfma_f32_16x16x32_bf16 v[22:25], v[154:157], v[194:197], v[22:25]
	v_mfma_f32_16x16x32_bf16 v[14:17], v[142:145], v[202:205], v[14:17]
	v_mfma_f32_16x16x32_bf16 v[6:9], v[154:157], v[202:205], v[6:9]
	v_mfma_f32_16x16x32_bf16 v[62:65], v[146:149], v[182:185], v[62:65]
	v_mfma_f32_16x16x32_bf16 v[54:57], v[158:161], v[182:185], v[54:57]
	v_mfma_f32_16x16x32_bf16 v[46:49], v[146:149], v[190:193], v[46:49]
	v_mfma_f32_16x16x32_bf16 v[38:41], v[158:161], v[190:193], v[38:41]
	v_mfma_f32_16x16x32_bf16 v[30:33], v[146:149], v[198:201], v[30:33]
	v_mfma_f32_16x16x32_bf16 v[22:25], v[158:161], v[198:201], v[22:25]
	v_mfma_f32_16x16x32_bf16 v[14:17], v[146:149], v[206:209], v[14:17]
	v_mfma_f32_16x16x32_bf16 v[6:9], v[158:161], v[206:209], v[6:9]
	v_mfma_f32_16x16x32_bf16 v[58:61], v[162:165], v[178:181], v[58:61]
	v_mfma_f32_16x16x32_bf16 v[50:53], v[170:173], v[178:181], v[50:53]
	v_mfma_f32_16x16x32_bf16 v[42:45], v[162:165], v[186:189], v[42:45]
	v_mfma_f32_16x16x32_bf16 v[34:37], v[170:173], v[186:189], v[34:37]
	v_mfma_f32_16x16x32_bf16 v[26:29], v[162:165], v[194:197], v[26:29]
	v_mfma_f32_16x16x32_bf16 v[18:21], v[170:173], v[194:197], v[18:21]
	v_mfma_f32_16x16x32_bf16 v[10:13], v[162:165], v[202:205], v[10:13]
	v_mfma_f32_16x16x32_bf16 v[2:5], v[170:173], v[202:205], v[2:5]
	v_mfma_f32_16x16x32_bf16 v[58:61], v[166:169], v[182:185], v[58:61]
	v_mfma_f32_16x16x32_bf16 v[50:53], v[174:177], v[182:185], v[50:53]
	v_mfma_f32_16x16x32_bf16 v[42:45], v[166:169], v[190:193], v[42:45]
	v_mfma_f32_16x16x32_bf16 v[34:37], v[174:177], v[190:193], v[34:37]
	v_mfma_f32_16x16x32_bf16 v[26:29], v[166:169], v[198:201], v[26:29]
	v_mfma_f32_16x16x32_bf16 v[18:21], v[174:177], v[198:201], v[18:21]
	v_mfma_f32_16x16x32_bf16 v[10:13], v[166:169], v[206:209], v[10:13]
	v_mfma_f32_16x16x32_bf16 v[2:5], v[174:177], v[206:209], v[2:5]
	s_barrier
	s_setprio 0
	s_add_i32 s10, 0, 0x18000
	s_add_i32 s11, 0, 0x1c000
	v_add_u32_e32 v158, s10, v150
	v_add_u32_e32 v174, s11, v150
	ds_read_b128 v[142:145], v158
	ds_read_b128 v[146:149], v158 offset:1024
	ds_read_b128 v[154:157], v158 offset:2048
	ds_read_b128 v[158:161], v158 offset:3072
	ds_read_b128 v[162:165], v174
	ds_read_b128 v[166:169], v174 offset:1024
	ds_read_b128 v[170:173], v174 offset:2048
	ds_read_b128 v[174:177], v174 offset:3072
	s_add_u32 s8, s40, 0x40000
	s_addc_u32 s9, s41, 0
	s_mov_b32 m0, s63
	ds_read_b128 v[178:181], v153 offset:32768
	ds_read_b128 v[182:185], v153 offset:33792
	ds_read_b128 v[186:189], v153 offset:34816
	ds_read_b128 v[190:193], v153 offset:35840
	ds_read_b128 v[194:197], v153 offset:36864
	ds_read_b128 v[198:201], v153 offset:37888
	ds_read_b128 v[202:205], v153 offset:38912
	ds_read_b128 v[206:209], v153 offset:39936
	global_load_lds_dwordx4 v136, s[8:9]
	s_mov_b32 m0, s64
	s_nop 0
	global_load_lds_dwordx4 v134, s[8:9]
	s_waitcnt vmcnt(8)
	s_waitcnt lgkmcnt(0)
	s_setprio 1
	s_barrier
	v_mfma_f32_16x16x32_bf16 v[126:129], v[142:145], v[178:181], v[126:129]
	v_mfma_f32_16x16x32_bf16 v[118:121], v[154:157], v[178:181], v[118:121]
	v_mfma_f32_16x16x32_bf16 v[110:113], v[142:145], v[186:189], v[110:113]
	v_mfma_f32_16x16x32_bf16 v[102:105], v[154:157], v[186:189], v[102:105]
	v_mfma_f32_16x16x32_bf16 v[94:97], v[142:145], v[194:197], v[94:97]
	v_mfma_f32_16x16x32_bf16 v[86:89], v[154:157], v[194:197], v[86:89]
	v_mfma_f32_16x16x32_bf16 v[78:81], v[142:145], v[202:205], v[78:81]
	v_mfma_f32_16x16x32_bf16 v[70:73], v[154:157], v[202:205], v[70:73]
	v_mfma_f32_16x16x32_bf16 v[126:129], v[146:149], v[182:185], v[126:129]
	v_mfma_f32_16x16x32_bf16 v[118:121], v[158:161], v[182:185], v[118:121]
	v_mfma_f32_16x16x32_bf16 v[110:113], v[146:149], v[190:193], v[110:113]
	v_mfma_f32_16x16x32_bf16 v[102:105], v[158:161], v[190:193], v[102:105]
	v_mfma_f32_16x16x32_bf16 v[94:97], v[146:149], v[198:201], v[94:97]
	v_mfma_f32_16x16x32_bf16 v[86:89], v[158:161], v[198:201], v[86:89]
	v_mfma_f32_16x16x32_bf16 v[78:81], v[146:149], v[206:209], v[78:81]
	v_mfma_f32_16x16x32_bf16 v[70:73], v[158:161], v[206:209], v[70:73]
	v_mfma_f32_16x16x32_bf16 v[122:125], v[162:165], v[178:181], v[122:125]
	v_mfma_f32_16x16x32_bf16 v[114:117], v[170:173], v[178:181], v[114:117]
	v_mfma_f32_16x16x32_bf16 v[106:109], v[162:165], v[186:189], v[106:109]
	v_mfma_f32_16x16x32_bf16 v[98:101], v[170:173], v[186:189], v[98:101]
	v_mfma_f32_16x16x32_bf16 v[90:93], v[162:165], v[194:197], v[90:93]
	v_mfma_f32_16x16x32_bf16 v[82:85], v[170:173], v[194:197], v[82:85]
	v_mfma_f32_16x16x32_bf16 v[74:77], v[162:165], v[202:205], v[74:77]
	v_mfma_f32_16x16x32_bf16 v[66:69], v[170:173], v[202:205], v[66:69]
	v_mfma_f32_16x16x32_bf16 v[122:125], v[166:169], v[182:185], v[122:125]
	v_mfma_f32_16x16x32_bf16 v[114:117], v[174:177], v[182:185], v[114:117]
	v_mfma_f32_16x16x32_bf16 v[106:109], v[166:169], v[190:193], v[106:109]
	v_mfma_f32_16x16x32_bf16 v[98:101], v[174:177], v[190:193], v[98:101]
	v_mfma_f32_16x16x32_bf16 v[90:93], v[166:169], v[198:201], v[90:93]
	v_mfma_f32_16x16x32_bf16 v[82:85], v[174:177], v[198:201], v[82:85]
	v_mfma_f32_16x16x32_bf16 v[74:77], v[166:169], v[206:209], v[74:77]
	v_mfma_f32_16x16x32_bf16 v[66:69], v[174:177], v[206:209], v[66:69]
	s_barrier
	s_setprio 0
	s_add_i32 s8, s10, s31
	v_lshl_add_u64 v[210:211], v[210:211], 0, s[82:83]
	s_mov_b32 m0, s8
	ds_read_b128 v[178:181], v153 offset:49152
	ds_read_b128 v[182:185], v153 offset:50176
	ds_read_b128 v[186:189], v153 offset:51200
	ds_read_b128 v[190:193], v153 offset:52224
	ds_read_b128 v[194:197], v153 offset:53248
	ds_read_b128 v[198:201], v153 offset:54272
	ds_read_b128 v[202:205], v153 offset:55296
	ds_read_b128 v[206:209], v153 offset:56320
	global_load_lds_dwordx4 v[210:211], off
	s_add_i32 m0, s8, 0x2000
	s_add_u32 s8, s28, 0x40080
	v_lshl_add_u64 v[210:211], v[212:213], 0, s[82:83]
	s_addc_u32 s9, s29, 0
	s_add_i32 s10, s11, s31
	global_load_lds_dwordx4 v[210:211], off
	s_mov_b32 m0, s10
	s_nop 0
	global_load_lds_dwordx4 v130, s[8:9]
	s_add_i32 m0, s10, 0x2000
	s_nop 0
	global_load_lds_dwordx4 v132, s[8:9]
	v_lshl_add_u64 v[210:211], v[214:215], 0, s[82:83]
	s_mov_b32 m0, s65
	s_nop 0
	global_load_lds_dwordx4 v[210:211], off
	v_lshl_add_u64 v[210:211], v[216:217], 0, s[82:83]
	s_mov_b32 m0, s66
	s_nop 0
	global_load_lds_dwordx4 v[210:211], off
	s_waitcnt vmcnt(8)
	s_waitcnt lgkmcnt(0)
	s_setprio 1
	s_barrier
	v_mfma_f32_16x16x32_bf16 v[62:65], v[142:145], v[178:181], v[62:65]
	v_mfma_f32_16x16x32_bf16 v[54:57], v[154:157], v[178:181], v[54:57]
	v_mfma_f32_16x16x32_bf16 v[46:49], v[142:145], v[186:189], v[46:49]
	v_mfma_f32_16x16x32_bf16 v[38:41], v[154:157], v[186:189], v[38:41]
	v_mfma_f32_16x16x32_bf16 v[30:33], v[142:145], v[194:197], v[30:33]
	v_mfma_f32_16x16x32_bf16 v[22:25], v[154:157], v[194:197], v[22:25]
	v_mfma_f32_16x16x32_bf16 v[14:17], v[142:145], v[202:205], v[14:17]
	v_mfma_f32_16x16x32_bf16 v[6:9], v[154:157], v[202:205], v[6:9]
	v_mfma_f32_16x16x32_bf16 v[62:65], v[146:149], v[182:185], v[62:65]
	v_mfma_f32_16x16x32_bf16 v[54:57], v[158:161], v[182:185], v[54:57]
	v_mfma_f32_16x16x32_bf16 v[46:49], v[146:149], v[190:193], v[46:49]
	v_mfma_f32_16x16x32_bf16 v[38:41], v[158:161], v[190:193], v[38:41]
	v_mfma_f32_16x16x32_bf16 v[30:33], v[146:149], v[198:201], v[30:33]
	v_mfma_f32_16x16x32_bf16 v[22:25], v[158:161], v[198:201], v[22:25]
	v_mfma_f32_16x16x32_bf16 v[14:17], v[146:149], v[206:209], v[14:17]
	v_mfma_f32_16x16x32_bf16 v[6:9], v[158:161], v[206:209], v[6:9]
	v_mfma_f32_16x16x32_bf16 v[58:61], v[162:165], v[178:181], v[58:61]
	v_mfma_f32_16x16x32_bf16 v[50:53], v[170:173], v[178:181], v[50:53]
	v_mfma_f32_16x16x32_bf16 v[42:45], v[162:165], v[186:189], v[42:45]
	v_mfma_f32_16x16x32_bf16 v[34:37], v[170:173], v[186:189], v[34:37]
	v_mfma_f32_16x16x32_bf16 v[26:29], v[162:165], v[194:197], v[26:29]
	v_mfma_f32_16x16x32_bf16 v[18:21], v[170:173], v[194:197], v[18:21]
	v_mfma_f32_16x16x32_bf16 v[10:13], v[162:165], v[202:205], v[10:13]
	v_mfma_f32_16x16x32_bf16 v[2:5], v[170:173], v[202:205], v[2:5]
	v_mfma_f32_16x16x32_bf16 v[58:61], v[166:169], v[182:185], v[58:61]
	v_mfma_f32_16x16x32_bf16 v[50:53], v[174:177], v[182:185], v[50:53]
	v_mfma_f32_16x16x32_bf16 v[42:45], v[166:169], v[190:193], v[42:45]
	v_mfma_f32_16x16x32_bf16 v[34:37], v[174:177], v[190:193], v[34:37]
	v_mfma_f32_16x16x32_bf16 v[26:29], v[166:169], v[198:201], v[26:29]
	v_mfma_f32_16x16x32_bf16 v[18:21], v[174:177], v[198:201], v[18:21]
	v_mfma_f32_16x16x32_bf16 v[10:13], v[166:169], v[206:209], v[10:13]
	v_mfma_f32_16x16x32_bf16 v[2:5], v[174:177], v[206:209], v[2:5]
	s_barrier
	s_setprio 0
	s_add_i32 s85, s85, 2
	s_add_u32 s58, s58, 0x100
	s_addc_u32 s59, s59, 0
	s_add_u32 s73, s73, 0x100
	s_addc_u32 s84, s84, 0
	s_cmp_gt_u32 s85, 13
	s_cbranch_scc0 .LBB0_50
	s_and_b64 vcc, exec, s[48:49]
	s_cbranch_vccz .LBB0_53
	s_barrier

.LBB0_75:
	s_add_i32 s41, s28, 2
	s_add_u32 s8, s60, 0x80
	s_addc_u32 s9, s61, 0
	s_add_i32 s10, 0, 0x10000
	s_cmp_eq_u32 s84, s28
	s_cselect_b32 s29, s47, s9
	s_cselect_b32 s28, s46, s8
	s_cselect_b32 s9, s59, s40
	s_cselect_b32 s8, s58, s7
	s_add_i32 s11, 0, 0x14000
	v_add_u32_e32 v126, s10, v1
	v_add_u32_e32 v160, s11, v1
	ds_read_b128 v[98:101], v126
	ds_read_b128 v[102:105], v126 offset:1024
	ds_read_b128 v[122:125], v126 offset:2048
	ds_read_b128 v[126:129], v126 offset:3072
	ds_read_b128 v[144:147], v160
	ds_read_b128 v[148:151], v160 offset:1024
	ds_read_b128 v[156:159], v160 offset:2048
	ds_read_b128 v[160:163], v160 offset:3072
	v_lshl_add_u64 v[206:207], s[60:61], 0, v[194:195]
	s_add_i32 m0, s66, 0xc000
	ds_read_b128 v[164:167], v231
	ds_read_b128 v[168:171], v231 offset:1024
	ds_read_b128 v[172:175], v231 offset:2048
	ds_read_b128 v[176:179], v231 offset:3072
	ds_read_b128 v[180:183], v231 offset:4096
	ds_read_b128 v[184:187], v231 offset:5120
	ds_read_b128 v[198:201], v231 offset:6144
	ds_read_b128 v[202:205], v231 offset:7168
	global_load_lds_dwordx4 v[206:207], off
	v_lshl_add_u64 v[206:207], s[60:61], 0, v[196:197]
	s_add_i32 m0, s66, 0xe000
	s_nop 0
	global_load_lds_dwordx4 v[206:207], off
	s_waitcnt vmcnt(8)
	s_waitcnt lgkmcnt(0)
	s_setprio 1
	s_barrier
	v_mfma_f32_16x16x32_bf16 v[152:155], v[98:101], v[164:167], v[152:155]
	v_mfma_f32_16x16x32_bf16 v[140:143], v[122:125], v[164:167], v[140:143]
	v_mfma_f32_16x16x32_bf16 v[118:121], v[98:101], v[172:175], v[118:121]
	v_mfma_f32_16x16x32_bf16 v[114:117], v[122:125], v[172:175], v[114:117]
	v_mfma_f32_16x16x32_bf16 v[94:97], v[98:101], v[180:183], v[94:97]
	v_mfma_f32_16x16x32_bf16 v[90:93], v[122:125], v[180:183], v[90:93]
	v_mfma_f32_16x16x32_bf16 v[78:81], v[98:101], v[198:201], v[78:81]
	v_mfma_f32_16x16x32_bf16 v[74:77], v[122:125], v[198:201], v[74:77]
	v_mfma_f32_16x16x32_bf16 v[152:155], v[102:105], v[168:171], v[152:155]
	v_mfma_f32_16x16x32_bf16 v[140:143], v[126:129], v[168:171], v[140:143]
	v_mfma_f32_16x16x32_bf16 v[118:121], v[102:105], v[176:179], v[118:121]
	v_mfma_f32_16x16x32_bf16 v[114:117], v[126:129], v[176:179], v[114:117]
	v_mfma_f32_16x16x32_bf16 v[94:97], v[102:105], v[184:187], v[94:97]
	v_mfma_f32_16x16x32_bf16 v[90:93], v[126:129], v[184:187], v[90:93]
	v_mfma_f32_16x16x32_bf16 v[78:81], v[102:105], v[202:205], v[78:81]
	v_mfma_f32_16x16x32_bf16 v[74:77], v[126:129], v[202:205], v[74:77]
	v_mfma_f32_16x16x32_bf16 v[136:139], v[144:147], v[164:167], v[136:139]
	v_mfma_f32_16x16x32_bf16 v[132:135], v[156:159], v[164:167], v[132:135]
	v_mfma_f32_16x16x32_bf16 v[110:113], v[144:147], v[172:175], v[110:113]
	v_mfma_f32_16x16x32_bf16 v[106:109], v[156:159], v[172:175], v[106:109]
	v_mfma_f32_16x16x32_bf16 v[86:89], v[144:147], v[180:183], v[86:89]
	v_mfma_f32_16x16x32_bf16 v[82:85], v[156:159], v[180:183], v[82:85]
	v_mfma_f32_16x16x32_bf16 v[70:73], v[144:147], v[198:201], v[70:73]
	v_mfma_f32_16x16x32_bf16 v[66:69], v[156:159], v[198:201], v[66:69]
	v_mfma_f32_16x16x32_bf16 v[136:139], v[148:151], v[168:171], v[136:139]
	v_mfma_f32_16x16x32_bf16 v[132:135], v[160:163], v[168:171], v[132:135]
	v_mfma_f32_16x16x32_bf16 v[110:113], v[148:151], v[176:179], v[110:113]
	v_mfma_f32_16x16x32_bf16 v[106:109], v[160:163], v[176:179], v[106:109]
	v_mfma_f32_16x16x32_bf16 v[86:89], v[148:151], v[184:187], v[86:89]
	v_mfma_f32_16x16x32_bf16 v[82:85], v[160:163], v[184:187], v[82:85]
	v_mfma_f32_16x16x32_bf16 v[70:73], v[148:151], v[202:205], v[70:73]
	v_mfma_f32_16x16x32_bf16 v[66:69], v[160:163], v[202:205], v[66:69]
	s_barrier
	s_setprio 0
	s_add_i32 s10, s10, s64
	v_lshl_add_u64 v[206:207], s[8:9], 0, v[130:131]
	s_mov_b32 m0, s10
	ds_read_b128 v[164:167], v231 offset:16384
	ds_read_b128 v[168:171], v231 offset:17408
	ds_read_b128 v[172:175], v231 offset:18432
	ds_read_b128 v[176:179], v231 offset:19456
	ds_read_b128 v[180:183], v231 offset:20480
	ds_read_b128 v[184:187], v231 offset:21504
	ds_read_b128 v[198:201], v231 offset:22528
	ds_read_b128 v[202:205], v231 offset:23552
	global_load_lds_dwordx4 v[206:207], off
	s_add_i32 m0, s10, 0x2000
	v_lshl_add_u64 v[208:209], s[8:9], 0, v[188:189]
	s_add_u32 s8, s8, s48
	s_addc_u32 s9, s9, 0
	s_add_i32 s10, s11, s64
	global_load_lds_dwordx4 v[208:209], off
	v_lshl_add_u64 v[210:211], s[8:9], 0, v[130:131]
	s_mov_b32 m0, s10
	v_lshl_add_u64 v[212:213], s[8:9], 0, v[188:189]
	global_load_lds_dwordx4 v[210:211], off
	s_add_i32 m0, s10, 0x2000
	v_lshl_add_u64 v[214:215], s[28:29], 0, v[192:193]
	global_load_lds_dwordx4 v[212:213], off
	s_mov_b32 m0, s66
	v_lshl_add_u64 v[216:217], s[28:29], 0, v[190:191]
	global_load_lds_dwordx4 v[214:215], off
	s_mov_b32 m0, s67
	s_nop 0
	global_load_lds_dwordx4 v[216:217], off
	s_waitcnt vmcnt(8)
	s_waitcnt lgkmcnt(0)
	s_setprio 1
	s_barrier
	v_mfma_f32_16x16x32_bf16 v[62:65], v[98:101], v[164:167], v[62:65]
	v_mfma_f32_16x16x32_bf16 v[58:61], v[122:125], v[164:167], v[58:61]
	v_mfma_f32_16x16x32_bf16 v[46:49], v[98:101], v[172:175], v[46:49]
	v_mfma_f32_16x16x32_bf16 v[42:45], v[122:125], v[172:175], v[42:45]
	v_mfma_f32_16x16x32_bf16 v[30:33], v[98:101], v[180:183], v[30:33]
	v_mfma_f32_16x16x32_bf16 v[26:29], v[122:125], v[180:183], v[26:29]
	v_mfma_f32_16x16x32_bf16 v[14:17], v[98:101], v[198:201], v[14:17]
	v_mfma_f32_16x16x32_bf16 v[10:13], v[122:125], v[198:201], v[10:13]
	v_mfma_f32_16x16x32_bf16 v[62:65], v[102:105], v[168:171], v[62:65]
	v_mfma_f32_16x16x32_bf16 v[58:61], v[126:129], v[168:171], v[58:61]
	v_mfma_f32_16x16x32_bf16 v[46:49], v[102:105], v[176:179], v[46:49]
	v_mfma_f32_16x16x32_bf16 v[42:45], v[126:129], v[176:179], v[42:45]
	v_mfma_f32_16x16x32_bf16 v[30:33], v[102:105], v[184:187], v[30:33]
	v_mfma_f32_16x16x32_bf16 v[26:29], v[126:129], v[184:187], v[26:29]
	v_mfma_f32_16x16x32_bf16 v[14:17], v[102:105], v[202:205], v[14:17]
	v_mfma_f32_16x16x32_bf16 v[10:13], v[126:129], v[202:205], v[10:13]
	v_mfma_f32_16x16x32_bf16 v[54:57], v[144:147], v[164:167], v[54:57]
	v_mfma_f32_16x16x32_bf16 v[50:53], v[156:159], v[164:167], v[50:53]
	v_mfma_f32_16x16x32_bf16 v[38:41], v[144:147], v[172:175], v[38:41]
	v_mfma_f32_16x16x32_bf16 v[34:37], v[156:159], v[172:175], v[34:37]
	v_mfma_f32_16x16x32_bf16 v[22:25], v[144:147], v[180:183], v[22:25]
	v_mfma_f32_16x16x32_bf16 v[18:21], v[156:159], v[180:183], v[18:21]
	v_mfma_f32_16x16x32_bf16 v[6:9], v[144:147], v[198:201], v[6:9]
	v_mfma_f32_16x16x32_bf16 v[2:5], v[156:159], v[198:201], v[2:5]
	v_mfma_f32_16x16x32_bf16 v[54:57], v[148:151], v[168:171], v[54:57]
	v_mfma_f32_16x16x32_bf16 v[50:53], v[160:163], v[168:171], v[50:53]
	v_mfma_f32_16x16x32_bf16 v[38:41], v[148:151], v[176:179], v[38:41]
	v_mfma_f32_16x16x32_bf16 v[34:37], v[160:163], v[176:179], v[34:37]
	v_mfma_f32_16x16x32_bf16 v[22:25], v[148:151], v[184:187], v[22:25]
	v_mfma_f32_16x16x32_bf16 v[18:21], v[160:163], v[184:187], v[18:21]
	v_mfma_f32_16x16x32_bf16 v[6:9], v[148:151], v[202:205], v[6:9]
	v_mfma_f32_16x16x32_bf16 v[2:5], v[160:163], v[202:205], v[2:5]
	s_barrier
	s_setprio 0
	s_add_i32 s10, 0, 0x18000
	s_add_i32 s11, 0, 0x1c000
	v_add_u32_e32 v126, s10, v1
	v_add_u32_e32 v160, s11, v1
	ds_read_b128 v[98:101], v126
	ds_read_b128 v[102:105], v126 offset:1024
	ds_read_b128 v[122:125], v126 offset:2048
	ds_read_b128 v[126:129], v126 offset:3072
	ds_read_b128 v[144:147], v160
	ds_read_b128 v[148:151], v160 offset:1024
	ds_read_b128 v[156:159], v160 offset:2048
	ds_read_b128 v[160:163], v160 offset:3072
	s_add_u32 s8, s28, s48
	s_addc_u32 s9, s29, 0
	s_mov_b32 m0, s68
	ds_read_b128 v[164:167], v231 offset:32768
	ds_read_b128 v[168:171], v231 offset:33792
	ds_read_b128 v[172:175], v231 offset:34816
	ds_read_b128 v[176:179], v231 offset:35840
	ds_read_b128 v[180:183], v231 offset:36864
	ds_read_b128 v[184:187], v231 offset:37888
	ds_read_b128 v[198:201], v231 offset:38912
	ds_read_b128 v[202:205], v231 offset:39936
	global_load_lds_dwordx4 v192, s[8:9]
	s_mov_b32 m0, s69
	s_nop 0
	global_load_lds_dwordx4 v190, s[8:9]
	s_waitcnt vmcnt(8)
	s_waitcnt lgkmcnt(0)
	s_setprio 1
	s_barrier
	v_mfma_f32_16x16x32_bf16 v[152:155], v[98:101], v[164:167], v[152:155]
	v_mfma_f32_16x16x32_bf16 v[140:143], v[122:125], v[164:167], v[140:143]
	v_mfma_f32_16x16x32_bf16 v[118:121], v[98:101], v[172:175], v[118:121]
	v_mfma_f32_16x16x32_bf16 v[114:117], v[122:125], v[172:175], v[114:117]
	v_mfma_f32_16x16x32_bf16 v[94:97], v[98:101], v[180:183], v[94:97]
	v_mfma_f32_16x16x32_bf16 v[90:93], v[122:125], v[180:183], v[90:93]
	v_mfma_f32_16x16x32_bf16 v[78:81], v[98:101], v[198:201], v[78:81]
	v_mfma_f32_16x16x32_bf16 v[74:77], v[122:125], v[198:201], v[74:77]
	v_mfma_f32_16x16x32_bf16 v[152:155], v[102:105], v[168:171], v[152:155]
	v_mfma_f32_16x16x32_bf16 v[140:143], v[126:129], v[168:171], v[140:143]
	v_mfma_f32_16x16x32_bf16 v[118:121], v[102:105], v[176:179], v[118:121]
	v_mfma_f32_16x16x32_bf16 v[114:117], v[126:129], v[176:179], v[114:117]
	v_mfma_f32_16x16x32_bf16 v[94:97], v[102:105], v[184:187], v[94:97]
	v_mfma_f32_16x16x32_bf16 v[90:93], v[126:129], v[184:187], v[90:93]
	v_mfma_f32_16x16x32_bf16 v[78:81], v[102:105], v[202:205], v[78:81]
	v_mfma_f32_16x16x32_bf16 v[74:77], v[126:129], v[202:205], v[74:77]
	v_mfma_f32_16x16x32_bf16 v[136:139], v[144:147], v[164:167], v[136:139]
	v_mfma_f32_16x16x32_bf16 v[132:135], v[156:159], v[164:167], v[132:135]
	v_mfma_f32_16x16x32_bf16 v[110:113], v[144:147], v[172:175], v[110:113]
	v_mfma_f32_16x16x32_bf16 v[106:109], v[156:159], v[172:175], v[106:109]
	v_mfma_f32_16x16x32_bf16 v[86:89], v[144:147], v[180:183], v[86:89]
	v_mfma_f32_16x16x32_bf16 v[82:85], v[156:159], v[180:183], v[82:85]
	v_mfma_f32_16x16x32_bf16 v[70:73], v[144:147], v[198:201], v[70:73]
	v_mfma_f32_16x16x32_bf16 v[66:69], v[156:159], v[198:201], v[66:69]
	v_mfma_f32_16x16x32_bf16 v[136:139], v[148:151], v[168:171], v[136:139]
	v_mfma_f32_16x16x32_bf16 v[132:135], v[160:163], v[168:171], v[132:135]
	v_mfma_f32_16x16x32_bf16 v[110:113], v[148:151], v[176:179], v[110:113]
	v_mfma_f32_16x16x32_bf16 v[106:109], v[160:163], v[176:179], v[106:109]
	v_mfma_f32_16x16x32_bf16 v[86:89], v[148:151], v[184:187], v[86:89]
	v_mfma_f32_16x16x32_bf16 v[82:85], v[160:163], v[184:187], v[82:85]
	v_mfma_f32_16x16x32_bf16 v[70:73], v[148:151], v[202:205], v[70:73]
	v_mfma_f32_16x16x32_bf16 v[66:69], v[160:163], v[202:205], v[66:69]
	s_barrier
	s_setprio 0
	s_add_i32 s8, s10, s64
	v_lshl_add_u64 v[206:207], v[206:207], 0, s[82:83]
	s_mov_b32 m0, s8
	ds_read_b128 v[164:167], v231 offset:49152
	ds_read_b128 v[168:171], v231 offset:50176
	ds_read_b128 v[172:175], v231 offset:51200
	ds_read_b128 v[176:179], v231 offset:52224
	ds_read_b128 v[180:183], v231 offset:53248
	ds_read_b128 v[184:187], v231 offset:54272
	ds_read_b128 v[198:201], v231 offset:55296
	ds_read_b128 v[202:205], v231 offset:56320
	global_load_lds_dwordx4 v[206:207], off
	v_lshl_add_u64 v[206:207], v[208:209], 0, s[82:83]
	s_add_i32 m0, s8, 0x2000
	s_add_i32 s8, s11, s64
	global_load_lds_dwordx4 v[206:207], off
	v_lshl_add_u64 v[206:207], v[210:211], 0, s[82:83]
	s_mov_b32 m0, s8
	s_nop 0
	global_load_lds_dwordx4 v[206:207], off
	v_lshl_add_u64 v[206:207], v[212:213], 0, s[82:83]
	s_add_i32 m0, s8, 0x2000
	s_nop 0
	global_load_lds_dwordx4 v[206:207], off
	v_lshl_add_u64 v[206:207], v[214:215], 0, s[82:83]
	s_mov_b32 m0, s85
	s_nop 0
	global_load_lds_dwordx4 v[206:207], off
	v_lshl_add_u64 v[206:207], v[216:217], 0, s[82:83]
	s_mov_b32 m0, s88
	s_nop 0
	global_load_lds_dwordx4 v[206:207], off
	s_waitcnt vmcnt(8)
	s_waitcnt lgkmcnt(0)
	s_setprio 1
	s_barrier
	v_mfma_f32_16x16x32_bf16 v[62:65], v[98:101], v[164:167], v[62:65]
	v_mfma_f32_16x16x32_bf16 v[58:61], v[122:125], v[164:167], v[58:61]
	v_mfma_f32_16x16x32_bf16 v[46:49], v[98:101], v[172:175], v[46:49]
	v_mfma_f32_16x16x32_bf16 v[42:45], v[122:125], v[172:175], v[42:45]
	v_mfma_f32_16x16x32_bf16 v[30:33], v[98:101], v[180:183], v[30:33]
	v_mfma_f32_16x16x32_bf16 v[26:29], v[122:125], v[180:183], v[26:29]
	v_mfma_f32_16x16x32_bf16 v[14:17], v[98:101], v[198:201], v[14:17]
	v_mfma_f32_16x16x32_bf16 v[10:13], v[122:125], v[198:201], v[10:13]
	v_mfma_f32_16x16x32_bf16 v[62:65], v[102:105], v[168:171], v[62:65]
	v_mfma_f32_16x16x32_bf16 v[58:61], v[126:129], v[168:171], v[58:61]
	v_mfma_f32_16x16x32_bf16 v[46:49], v[102:105], v[176:179], v[46:49]
	v_mfma_f32_16x16x32_bf16 v[42:45], v[126:129], v[176:179], v[42:45]
	v_mfma_f32_16x16x32_bf16 v[30:33], v[102:105], v[184:187], v[30:33]
	v_mfma_f32_16x16x32_bf16 v[26:29], v[126:129], v[184:187], v[26:29]
	v_mfma_f32_16x16x32_bf16 v[14:17], v[102:105], v[202:205], v[14:17]
	v_mfma_f32_16x16x32_bf16 v[10:13], v[126:129], v[202:205], v[10:13]
	v_mfma_f32_16x16x32_bf16 v[54:57], v[144:147], v[164:167], v[54:57]
	v_mfma_f32_16x16x32_bf16 v[50:53], v[156:159], v[164:167], v[50:53]
	v_mfma_f32_16x16x32_bf16 v[38:41], v[144:147], v[172:175], v[38:41]
	v_mfma_f32_16x16x32_bf16 v[34:37], v[156:159], v[172:175], v[34:37]
	v_mfma_f32_16x16x32_bf16 v[22:25], v[144:147], v[180:183], v[22:25]
	v_mfma_f32_16x16x32_bf16 v[18:21], v[156:159], v[180:183], v[18:21]
	v_mfma_f32_16x16x32_bf16 v[6:9], v[144:147], v[198:201], v[6:9]
	v_mfma_f32_16x16x32_bf16 v[2:5], v[156:159], v[198:201], v[2:5]
	v_mfma_f32_16x16x32_bf16 v[54:57], v[148:151], v[168:171], v[54:57]
	v_mfma_f32_16x16x32_bf16 v[50:53], v[160:163], v[168:171], v[50:53]
	v_mfma_f32_16x16x32_bf16 v[38:41], v[148:151], v[176:179], v[38:41]
	v_mfma_f32_16x16x32_bf16 v[34:37], v[160:163], v[176:179], v[34:37]
	v_mfma_f32_16x16x32_bf16 v[22:25], v[148:151], v[184:187], v[22:25]
	v_mfma_f32_16x16x32_bf16 v[18:21], v[160:163], v[184:187], v[18:21]
	v_mfma_f32_16x16x32_bf16 v[6:9], v[148:151], v[202:205], v[6:9]
	v_mfma_f32_16x16x32_bf16 v[2:5], v[160:163], v[202:205], v[2:5]
	s_barrier
	s_setprio 0
	s_add_u32 s60, s60, 0x100
	s_addc_u32 s61, s61, 0
	s_add_u32 s7, s7, 0x100
	s_addc_u32 s40, s40, 0
	s_cmp_ge_u32 s41, s73
	s_mov_b32 s28, s41
	s_cbranch_scc0 .LBB0_75
	s_and_b64 vcc, exec, s[54:55]
	s_cbranch_vccz .LBB0_78
	s_barrier

.LBB0_491:
	s_and_b32 s10, s42, 3
	s_add_i32 m0, s62, 0x18000
	v_lshl_add_u64 v[8:9], v[8:9], 0, s[82:83]
	s_lshl_b32 s11, s6, 13
	s_lshl_b32 s42, s10, 12
	s_waitcnt vmcnt(2)
	s_barrier
	global_load_lds_dwordx4 v[8:9], off
	v_lshl_add_u64 v[6:7], v[6:7], 0, s[82:83]
	s_add_i32 m0, s62, 0x1a000
	s_add_i32 s66, s62, 0x8000
	s_add_i32 s67, s62, 0xa000
	global_load_lds_dwordx4 v[6:7], off
	v_lshl_add_u64 v[2:3], v[2:3], 0, s[82:83]
	s_mov_b32 m0, s66
	s_add_u32 s8, s28, 0x40080
	global_load_lds_dwordx4 v[2:3], off
	v_lshl_add_u64 v[2:3], v[4:5], 0, s[82:83]
	s_mov_b32 m0, s67
	s_addc_u32 s9, s29, 0
	global_load_lds_dwordx4 v[2:3], off
	s_add_i32 m0, s62, 0x1c000
	s_nop 0
	global_load_lds_dwordx4 v130, s[8:9]
	s_add_i32 m0, s62, 0x1e000
	v_lshrrev_b32_e32 v1, 1, v242
	global_load_lds_dwordx4 v132, s[8:9]
	v_and_b32_e32 v2, 15, v242
	v_and_b32_e32 v3, 24, v1
	v_lshlrev_b32_e32 v1, 1, v3
	v_lshlrev_b32_e32 v4, 2, v2
	v_lshl_or_b32 v1, v2, 6, v1
	v_and_b32_e32 v5, 32, v4
	v_bitop3_b32 v6, v1, s11, v5 bitop3:0xde
	v_bitop3_b32 v1, s42, v1, v5 bitop3:0xf6
	s_cmpk_lt_u32 s7, 0x100
	v_cmp_lt_u32_e64 s[42:43], 7, v2
	s_cselect_b64 s[50:51], -1, 0
	s_lshl_b32 s7, s10, 6
	v_cndmask_b32_e64 v2, 0, 32, s[42:43]
	v_or3_b32 v144, s7, v2, v3
	v_lshlrev_b32_e32 v2, 14, v14
	v_and_b32_e32 v2, 0xffff8000, v2
	v_lshl_add_u32 v2, v13, 11, v2
	v_and_b32_e32 v3, 1, v14
	v_lshl_or_b32 v2, v3, 6, v2
	v_and_b32_e32 v5, 7, v242
	v_lshl_add_u32 v138, v15, 1, v2
	v_lshlrev_b32_e32 v2, 14, v10
	v_lshl_or_b32 v142, s6, 6, v5
	s_lshl_b32 s6, s6, 8
	v_and_b32_e32 v2, 0xffff8000, v2
	s_waitcnt vmcnt(6)
	s_add_i32 s6, s6, 0
	v_lshl_add_u32 v2, v11, 11, v2
	v_and_b32_e32 v3, 1, v10
	s_add_i32 s6, s6, 0x20000
	v_lshl_or_b32 v2, v3, 6, v2
	v_readlane_b32 s8, v253, 39
	s_mov_b32 s68, 0
	s_ashr_i32 s69, s4, 31
	v_add_u32_e32 v143, s6, v4
	v_mov_b32_e32 v139, v131
	v_lshl_add_u32 v140, v12, 1, v2
	v_mov_b32_e32 v141, v131
	v_add_u32_e32 v145, 0, v6
	v_readlane_b32 s7, v251, 24
	s_mov_b32 s6, s8
	s_barrier
	v_readlane_b32 s9, v253, 40
	s_branch .LBB0_494

.LBB0_497:
	s_add_u32 s8, s60, 0xfffc0080
	s_addc_u32 s9, s61, -1
	s_add_i32 s10, 0, 0x10000
	s_cmp_eq_u32 s84, 12
	s_cselect_b32 s41, s55, s9
	s_cselect_b32 s40, s72, s8
	s_cselect_b32 s29, s53, s77
	s_cselect_b32 s28, s73, s76
	s_add_i32 s11, 0, 0x14000
	v_add_u32_e32 v158, s10, v1
	v_add_u32_e32 v174, s11, v1
	ds_read_b128 v[146:149], v158
	ds_read_b128 v[150:153], v158 offset:1024
	ds_read_b128 v[154:157], v158 offset:2048
	ds_read_b128 v[158:161], v158 offset:3072
	ds_read_b128 v[162:165], v174
	ds_read_b128 v[166:169], v174 offset:1024
	ds_read_b128 v[170:173], v174 offset:2048
	ds_read_b128 v[174:177], v174 offset:3072
	s_add_i32 m0, s62, 0xc000
	ds_read_b128 v[178:181], v145
	ds_read_b128 v[182:185], v145 offset:1024
	ds_read_b128 v[186:189], v145 offset:2048
	ds_read_b128 v[190:193], v145 offset:3072
	ds_read_b128 v[194:197], v145 offset:4096
	ds_read_b128 v[198:201], v145 offset:5120
	ds_read_b128 v[202:205], v145 offset:6144
	ds_read_b128 v[206:209], v145 offset:7168
	global_load_lds_dwordx4 v138, s[60:61]
	s_add_i32 m0, s62, 0xe000
	s_nop 0
	global_load_lds_dwordx4 v140, s[60:61]
	s_waitcnt vmcnt(8)
	s_waitcnt lgkmcnt(0)
	s_setprio 1
	s_barrier
	v_mfma_f32_16x16x32_bf16 v[126:129], v[146:149], v[178:181], v[126:129]
	v_mfma_f32_16x16x32_bf16 v[122:125], v[154:157], v[178:181], v[122:125]
	v_mfma_f32_16x16x32_bf16 v[110:113], v[146:149], v[186:189], v[110:113]
	v_mfma_f32_16x16x32_bf16 v[106:109], v[154:157], v[186:189], v[106:109]
	v_mfma_f32_16x16x32_bf16 v[94:97], v[146:149], v[194:197], v[94:97]
	v_mfma_f32_16x16x32_bf16 v[90:93], v[154:157], v[194:197], v[90:93]
	v_mfma_f32_16x16x32_bf16 v[78:81], v[146:149], v[202:205], v[78:81]
	v_mfma_f32_16x16x32_bf16 v[74:77], v[154:157], v[202:205], v[74:77]
	v_mfma_f32_16x16x32_bf16 v[126:129], v[150:153], v[182:185], v[126:129]
	v_mfma_f32_16x16x32_bf16 v[122:125], v[158:161], v[182:185], v[122:125]
	v_mfma_f32_16x16x32_bf16 v[110:113], v[150:153], v[190:193], v[110:113]
	v_mfma_f32_16x16x32_bf16 v[106:109], v[158:161], v[190:193], v[106:109]
	v_mfma_f32_16x16x32_bf16 v[94:97], v[150:153], v[198:201], v[94:97]
	v_mfma_f32_16x16x32_bf16 v[90:93], v[158:161], v[198:201], v[90:93]
	v_mfma_f32_16x16x32_bf16 v[78:81], v[150:153], v[206:209], v[78:81]
	v_mfma_f32_16x16x32_bf16 v[74:77], v[158:161], v[206:209], v[74:77]
	v_mfma_f32_16x16x32_bf16 v[118:121], v[162:165], v[178:181], v[118:121]
	v_mfma_f32_16x16x32_bf16 v[114:117], v[170:173], v[178:181], v[114:117]
	v_mfma_f32_16x16x32_bf16 v[102:105], v[162:165], v[186:189], v[102:105]
	v_mfma_f32_16x16x32_bf16 v[98:101], v[170:173], v[186:189], v[98:101]
	v_mfma_f32_16x16x32_bf16 v[86:89], v[162:165], v[194:197], v[86:89]
	v_mfma_f32_16x16x32_bf16 v[82:85], v[170:173], v[194:197], v[82:85]
	v_mfma_f32_16x16x32_bf16 v[70:73], v[162:165], v[202:205], v[70:73]
	v_mfma_f32_16x16x32_bf16 v[66:69], v[170:173], v[202:205], v[66:69]
	v_mfma_f32_16x16x32_bf16 v[118:121], v[166:169], v[182:185], v[118:121]
	v_mfma_f32_16x16x32_bf16 v[114:117], v[174:177], v[182:185], v[114:117]
	v_mfma_f32_16x16x32_bf16 v[102:105], v[166:169], v[190:193], v[102:105]
	v_mfma_f32_16x16x32_bf16 v[98:101], v[174:177], v[190:193], v[98:101]
	v_mfma_f32_16x16x32_bf16 v[86:89], v[166:169], v[198:201], v[86:89]
	v_mfma_f32_16x16x32_bf16 v[82:85], v[174:177], v[198:201], v[82:85]
	v_mfma_f32_16x16x32_bf16 v[70:73], v[166:169], v[206:209], v[70:73]
	v_mfma_f32_16x16x32_bf16 v[66:69], v[174:177], v[206:209], v[66:69]
	s_barrier
	s_setprio 0
	s_add_i32 s8, s10, s34
	v_lshl_add_u64 v[210:211], s[28:29], 0, v[130:131]
	s_mov_b32 m0, s8
	ds_read_b128 v[178:181], v145 offset:16384
	ds_read_b128 v[182:185], v145 offset:17408
	ds_read_b128 v[186:189], v145 offset:18432
	ds_read_b128 v[190:193], v145 offset:19456
	ds_read_b128 v[194:197], v145 offset:20480
	ds_read_b128 v[198:201], v145 offset:21504
	ds_read_b128 v[202:205], v145 offset:22528
	ds_read_b128 v[206:209], v145 offset:23552
	global_load_lds_dwordx4 v[210:211], off
	s_add_i32 m0, s8, 0x2000
	s_add_u32 s8, s28, 0x40000
	v_lshl_add_u64 v[212:213], s[28:29], 0, v[132:133]
	s_addc_u32 s9, s29, 0
	s_add_i32 s10, s11, s34
	global_load_lds_dwordx4 v[212:213], off
	s_mov_b32 m0, s10
	v_lshl_add_u64 v[216:217], s[40:41], 0, v[134:135]
	global_load_lds_dwordx4 v130, s[8:9]
	s_add_i32 m0, s10, 0x2000
	s_nop 0
	global_load_lds_dwordx4 v132, s[8:9]
	v_lshl_add_u64 v[214:215], s[40:41], 0, v[136:137]
	s_mov_b32 m0, s62
	s_nop 0
	global_load_lds_dwordx4 v[214:215], off
	s_mov_b32 m0, s63
	s_nop 0
	global_load_lds_dwordx4 v[216:217], off
	s_waitcnt vmcnt(8)
	s_waitcnt lgkmcnt(0)
	s_setprio 1
	s_barrier
	v_mfma_f32_16x16x32_bf16 v[62:65], v[146:149], v[178:181], v[62:65]
	v_mfma_f32_16x16x32_bf16 v[58:61], v[154:157], v[178:181], v[58:61]
	v_mfma_f32_16x16x32_bf16 v[46:49], v[146:149], v[186:189], v[46:49]
	v_mfma_f32_16x16x32_bf16 v[42:45], v[154:157], v[186:189], v[42:45]
	v_mfma_f32_16x16x32_bf16 v[30:33], v[146:149], v[194:197], v[30:33]
	v_mfma_f32_16x16x32_bf16 v[26:29], v[154:157], v[194:197], v[26:29]
	v_mfma_f32_16x16x32_bf16 v[14:17], v[146:149], v[202:205], v[14:17]
	v_mfma_f32_16x16x32_bf16 v[10:13], v[154:157], v[202:205], v[10:13]
	v_mfma_f32_16x16x32_bf16 v[62:65], v[150:153], v[182:185], v[62:65]
	v_mfma_f32_16x16x32_bf16 v[58:61], v[158:161], v[182:185], v[58:61]
	v_mfma_f32_16x16x32_bf16 v[46:49], v[150:153], v[190:193], v[46:49]
	v_mfma_f32_16x16x32_bf16 v[42:45], v[158:161], v[190:193], v[42:45]
	v_mfma_f32_16x16x32_bf16 v[30:33], v[150:153], v[198:201], v[30:33]
	v_mfma_f32_16x16x32_bf16 v[26:29], v[158:161], v[198:201], v[26:29]
	v_mfma_f32_16x16x32_bf16 v[14:17], v[150:153], v[206:209], v[14:17]
	v_mfma_f32_16x16x32_bf16 v[10:13], v[158:161], v[206:209], v[10:13]
	v_mfma_f32_16x16x32_bf16 v[54:57], v[162:165], v[178:181], v[54:57]
	v_mfma_f32_16x16x32_bf16 v[50:53], v[170:173], v[178:181], v[50:53]
	v_mfma_f32_16x16x32_bf16 v[38:41], v[162:165], v[186:189], v[38:41]
	v_mfma_f32_16x16x32_bf16 v[34:37], v[170:173], v[186:189], v[34:37]
	v_mfma_f32_16x16x32_bf16 v[22:25], v[162:165], v[194:197], v[22:25]
	v_mfma_f32_16x16x32_bf16 v[18:21], v[170:173], v[194:197], v[18:21]
	v_mfma_f32_16x16x32_bf16 v[6:9], v[162:165], v[202:205], v[6:9]
	v_mfma_f32_16x16x32_bf16 v[2:5], v[170:173], v[202:205], v[2:5]
	v_mfma_f32_16x16x32_bf16 v[54:57], v[166:169], v[182:185], v[54:57]
	v_mfma_f32_16x16x32_bf16 v[50:53], v[174:177], v[182:185], v[50:53]
	v_mfma_f32_16x16x32_bf16 v[38:41], v[166:169], v[190:193], v[38:41]
	v_mfma_f32_16x16x32_bf16 v[34:37], v[174:177], v[190:193], v[34:37]
	v_mfma_f32_16x16x32_bf16 v[22:25], v[166:169], v[198:201], v[22:25]
	v_mfma_f32_16x16x32_bf16 v[18:21], v[174:177], v[198:201], v[18:21]
	v_mfma_f32_16x16x32_bf16 v[6:9], v[166:169], v[206:209], v[6:9]
	v_mfma_f32_16x16x32_bf16 v[2:5], v[174:177], v[206:209], v[2:5]
	s_barrier
	s_setprio 0
	s_add_i32 s10, 0, 0x18000
	s_add_i32 s11, 0, 0x1c000
	v_add_u32_e32 v158, s10, v1
	v_add_u32_e32 v174, s11, v1
	ds_read_b128 v[146:149], v158
	ds_read_b128 v[150:153], v158 offset:1024
	ds_read_b128 v[154:157], v158 offset:2048
	ds_read_b128 v[158:161], v158 offset:3072
	ds_read_b128 v[162:165], v174
	ds_read_b128 v[166:169], v174 offset:1024
	ds_read_b128 v[170:173], v174 offset:2048
	ds_read_b128 v[174:177], v174 offset:3072
	s_add_u32 s8, s40, 0x40000
	s_addc_u32 s9, s41, 0
	s_mov_b32 m0, s64
	ds_read_b128 v[178:181], v145 offset:32768
	ds_read_b128 v[182:185], v145 offset:33792
	ds_read_b128 v[186:189], v145 offset:34816
	ds_read_b128 v[190:193], v145 offset:35840
	ds_read_b128 v[194:197], v145 offset:36864
	ds_read_b128 v[198:201], v145 offset:37888
	ds_read_b128 v[202:205], v145 offset:38912
	ds_read_b128 v[206:209], v145 offset:39936
	global_load_lds_dwordx4 v136, s[8:9]
	s_mov_b32 m0, s65
	s_nop 0
	global_load_lds_dwordx4 v134, s[8:9]
	s_waitcnt vmcnt(8)
	s_waitcnt lgkmcnt(0)
	s_setprio 1
	s_barrier
	v_mfma_f32_16x16x32_bf16 v[126:129], v[146:149], v[178:181], v[126:129]
	v_mfma_f32_16x16x32_bf16 v[122:125], v[154:157], v[178:181], v[122:125]
	v_mfma_f32_16x16x32_bf16 v[110:113], v[146:149], v[186:189], v[110:113]
	v_mfma_f32_16x16x32_bf16 v[106:109], v[154:157], v[186:189], v[106:109]
	v_mfma_f32_16x16x32_bf16 v[94:97], v[146:149], v[194:197], v[94:97]
	v_mfma_f32_16x16x32_bf16 v[90:93], v[154:157], v[194:197], v[90:93]
	v_mfma_f32_16x16x32_bf16 v[78:81], v[146:149], v[202:205], v[78:81]
	v_mfma_f32_16x16x32_bf16 v[74:77], v[154:157], v[202:205], v[74:77]
	v_mfma_f32_16x16x32_bf16 v[126:129], v[150:153], v[182:185], v[126:129]
	v_mfma_f32_16x16x32_bf16 v[122:125], v[158:161], v[182:185], v[122:125]
	v_mfma_f32_16x16x32_bf16 v[110:113], v[150:153], v[190:193], v[110:113]
	v_mfma_f32_16x16x32_bf16 v[106:109], v[158:161], v[190:193], v[106:109]
	v_mfma_f32_16x16x32_bf16 v[94:97], v[150:153], v[198:201], v[94:97]
	v_mfma_f32_16x16x32_bf16 v[90:93], v[158:161], v[198:201], v[90:93]
	v_mfma_f32_16x16x32_bf16 v[78:81], v[150:153], v[206:209], v[78:81]
	v_mfma_f32_16x16x32_bf16 v[74:77], v[158:161], v[206:209], v[74:77]
	v_mfma_f32_16x16x32_bf16 v[118:121], v[162:165], v[178:181], v[118:121]
	v_mfma_f32_16x16x32_bf16 v[114:117], v[170:173], v[178:181], v[114:117]
	v_mfma_f32_16x16x32_bf16 v[102:105], v[162:165], v[186:189], v[102:105]
	v_mfma_f32_16x16x32_bf16 v[98:101], v[170:173], v[186:189], v[98:101]
	v_mfma_f32_16x16x32_bf16 v[86:89], v[162:165], v[194:197], v[86:89]
	v_mfma_f32_16x16x32_bf16 v[82:85], v[170:173], v[194:197], v[82:85]
	v_mfma_f32_16x16x32_bf16 v[70:73], v[162:165], v[202:205], v[70:73]
	v_mfma_f32_16x16x32_bf16 v[66:69], v[170:173], v[202:205], v[66:69]
	v_mfma_f32_16x16x32_bf16 v[118:121], v[166:169], v[182:185], v[118:121]
	v_mfma_f32_16x16x32_bf16 v[114:117], v[174:177], v[182:185], v[114:117]
	v_mfma_f32_16x16x32_bf16 v[102:105], v[166:169], v[190:193], v[102:105]
	v_mfma_f32_16x16x32_bf16 v[98:101], v[174:177], v[190:193], v[98:101]
	v_mfma_f32_16x16x32_bf16 v[86:89], v[166:169], v[198:201], v[86:89]
	v_mfma_f32_16x16x32_bf16 v[82:85], v[174:177], v[198:201], v[82:85]
	v_mfma_f32_16x16x32_bf16 v[70:73], v[166:169], v[206:209], v[70:73]
	v_mfma_f32_16x16x32_bf16 v[66:69], v[174:177], v[206:209], v[66:69]
	s_barrier
	s_setprio 0
	s_add_i32 s8, s10, s34
	v_lshl_add_u64 v[210:211], v[210:211], 0, s[82:83]
	s_mov_b32 m0, s8
	ds_read_b128 v[178:181], v145 offset:49152
	ds_read_b128 v[182:185], v145 offset:50176
	ds_read_b128 v[186:189], v145 offset:51200
	ds_read_b128 v[190:193], v145 offset:52224
	ds_read_b128 v[194:197], v145 offset:53248
	ds_read_b128 v[198:201], v145 offset:54272
	ds_read_b128 v[202:205], v145 offset:55296
	ds_read_b128 v[206:209], v145 offset:56320
	global_load_lds_dwordx4 v[210:211], off
	s_add_i32 m0, s8, 0x2000
	s_add_u32 s8, s28, 0x40080
	v_lshl_add_u64 v[210:211], v[212:213], 0, s[82:83]
	s_addc_u32 s9, s29, 0
	s_add_i32 s10, s11, s34
	global_load_lds_dwordx4 v[210:211], off
	s_mov_b32 m0, s10
	s_nop 0
	global_load_lds_dwordx4 v130, s[8:9]
	s_add_i32 m0, s10, 0x2000
	s_nop 0
	global_load_lds_dwordx4 v132, s[8:9]
	v_lshl_add_u64 v[210:211], v[214:215], 0, s[82:83]
	s_mov_b32 m0, s66
	s_nop 0
	global_load_lds_dwordx4 v[210:211], off
	v_lshl_add_u64 v[210:211], v[216:217], 0, s[82:83]
	s_mov_b32 m0, s67
	s_nop 0
	global_load_lds_dwordx4 v[210:211], off
	s_waitcnt vmcnt(8)
	s_waitcnt lgkmcnt(0)
	s_setprio 1
	s_barrier
	v_mfma_f32_16x16x32_bf16 v[62:65], v[146:149], v[178:181], v[62:65]
	v_mfma_f32_16x16x32_bf16 v[58:61], v[154:157], v[178:181], v[58:61]
	v_mfma_f32_16x16x32_bf16 v[46:49], v[146:149], v[186:189], v[46:49]
	v_mfma_f32_16x16x32_bf16 v[42:45], v[154:157], v[186:189], v[42:45]
	v_mfma_f32_16x16x32_bf16 v[30:33], v[146:149], v[194:197], v[30:33]
	v_mfma_f32_16x16x32_bf16 v[26:29], v[154:157], v[194:197], v[26:29]
	v_mfma_f32_16x16x32_bf16 v[14:17], v[146:149], v[202:205], v[14:17]
	v_mfma_f32_16x16x32_bf16 v[10:13], v[154:157], v[202:205], v[10:13]
	v_mfma_f32_16x16x32_bf16 v[62:65], v[150:153], v[182:185], v[62:65]
	v_mfma_f32_16x16x32_bf16 v[58:61], v[158:161], v[182:185], v[58:61]
	v_mfma_f32_16x16x32_bf16 v[46:49], v[150:153], v[190:193], v[46:49]
	v_mfma_f32_16x16x32_bf16 v[42:45], v[158:161], v[190:193], v[42:45]
	v_mfma_f32_16x16x32_bf16 v[30:33], v[150:153], v[198:201], v[30:33]
	v_mfma_f32_16x16x32_bf16 v[26:29], v[158:161], v[198:201], v[26:29]
	v_mfma_f32_16x16x32_bf16 v[14:17], v[150:153], v[206:209], v[14:17]
	v_mfma_f32_16x16x32_bf16 v[10:13], v[158:161], v[206:209], v[10:13]
	v_mfma_f32_16x16x32_bf16 v[54:57], v[162:165], v[178:181], v[54:57]
	v_mfma_f32_16x16x32_bf16 v[50:53], v[170:173], v[178:181], v[50:53]
	v_mfma_f32_16x16x32_bf16 v[38:41], v[162:165], v[186:189], v[38:41]
	v_mfma_f32_16x16x32_bf16 v[34:37], v[170:173], v[186:189], v[34:37]
	v_mfma_f32_16x16x32_bf16 v[22:25], v[162:165], v[194:197], v[22:25]
	v_mfma_f32_16x16x32_bf16 v[18:21], v[170:173], v[194:197], v[18:21]
	v_mfma_f32_16x16x32_bf16 v[6:9], v[162:165], v[202:205], v[6:9]
	v_mfma_f32_16x16x32_bf16 v[2:5], v[170:173], v[202:205], v[2:5]
	v_mfma_f32_16x16x32_bf16 v[54:57], v[166:169], v[182:185], v[54:57]
	v_mfma_f32_16x16x32_bf16 v[50:53], v[174:177], v[182:185], v[50:53]
	v_mfma_f32_16x16x32_bf16 v[38:41], v[166:169], v[190:193], v[38:41]
	v_mfma_f32_16x16x32_bf16 v[34:37], v[174:177], v[190:193], v[34:37]
	v_mfma_f32_16x16x32_bf16 v[22:25], v[166:169], v[198:201], v[22:25]
	v_mfma_f32_16x16x32_bf16 v[18:21], v[174:177], v[198:201], v[18:21]
	v_mfma_f32_16x16x32_bf16 v[6:9], v[166:169], v[206:209], v[6:9]
	v_mfma_f32_16x16x32_bf16 v[2:5], v[174:177], v[206:209], v[2:5]
	s_barrier
	s_setprio 0
	s_add_i32 s84, s84, 2
	s_add_u32 s60, s60, 0x100
	s_addc_u32 s61, s61, 0
	s_add_u32 s76, s76, 0x100
	s_addc_u32 s77, s77, 0
	s_cmp_gt_u32 s84, 13
	s_cbranch_scc0 .LBB0_497
	s_and_b64 vcc, exec, s[50:51]
	s_cbranch_vccz .LBB0_500
	s_barrier
